# G2 epilogue: f32 residual rows stored with the default cache policy instead of nt
# speedup vs baseline: 1.0068x; 1.0068x over previous
; #define NTL(p) __builtin_nontemporal_load((const f32x4*)(p))
; #define NTS(v, p) __builtin_nontemporal_store((v), (f32x4*)(p))
; __device__ __forceinline__ unsigned cvt_pk_bf16(float lo, float hi) { unsigned r; asm volatile("v_cvt_pk_bf16_f32 %0, %1, %2" : "=v"(r) : "v"(lo), "v"(hi)); return r; }
;     __device__ __forceinline__ void operator()(AccT& acc, const Unit& u, int wr, int wc, int fr, int fq) const {
;     ...
;         const int row0 = u.pm * 256 + wr * 64 + fr, col0 = u.pn * 256 + wc * 32 + 8 * fq;
;         f32x4 xv[2][4];
;         { const int row = row0; const float* xr = (row < HALF_TOK ? x0 + (size_t)row * DM : x1 + (size_t)(row - HALF_TOK) * DM) + col0;
;           xv[0][0] = NTL(xr); xv[0][1] = NTL(xr + 4); xv[0][2] = NTL(xr + 128); xv[0][3] = NTL(xr + 132); }
; #pragma unroll
;         for (int r = 0; r < 8; ++r) { const int ai = r >> 2, m = r & 3; const int row = row0 + ai * 128 + m * 16;
;             if (r < 7) { const int rn = row0 + ((r + 1) >> 2) * 128 + ((r + 1) & 3) * 16; const float* xr = (rn < HALF_TOK ? x0 + (size_t)rn * DM : x1 + (size_t)(rn - HALF_TOK) * DM) + col0;
;                 xv[(r + 1) & 1][0] = NTL(xr); xv[(r + 1) & 1][1] = NTL(xr + 4); xv[(r + 1) & 1][2] = NTL(xr + 128); xv[(r + 1) & 1][3] = NTL(xr + 132); }
;             float* hr = H + (size_t)row * DM + col0; float ss = 0.f;
; #pragma unroll
;             for (int bj = 0; bj < 2; ++bj) {
;                 f32x4 v0 = acc[ai][bj][m][0] + xv[r & 1][2 * bj], v1 = acc[ai][bj][m][1] + xv[r & 1][2 * bj + 1];
;                 NTS(v0, hr + bj * 128); NTS(v1, hr + bj * 128 + 4);
;                 u32x4 w; w.x = cvt_pk_bf16(v0[0], v0[1]); w.y = cvt_pk_bf16(v0[2], v0[3]); w.z = cvt_pk_bf16(v1[0], v1[1]); w.w = cvt_pk_bf16(v1[2], v1[3]);
;                 *(u32x4*)(HB + (size_t)row * DM + col0 + bj * 128) = w;
; #pragma unroll
;                 for (int j = 0; j < 4; ++j) ss += v0[j] * v0[j] + v1[j] * v1[j]; }
;             ss += __shfl_xor(ss, 16); ss += __shfl_xor(ss, 32);
;             if (fq == 0) unsafeAtomicAdd(rss + row, ss); __builtin_amdgcn_sched_barrier(0); }
.LBB0_48:
	s_lshl_b32 s16, s76, 8
	v_mov_b32_e32 v130, v164
	s_add_i32 s16, s16, s50
	v_mov_b32_e32 v134, v165
	v_add_u32_e32 v158, s16, v130
	s_lshl_b32 s16, s77, 8
	s_or_b32 s16, s16, s51
	v_readlane_b32 s60, v254, 34
	v_lshl_add_u32 v156, v134, 3, s16
	s_movk_i32 s16, 0x4000
	v_cmp_gt_i32_e32 vcc, s16, v158
	v_add_u32_e32 v130, 0xffffc000, v158
	v_ashrrev_i32_e32 v159, 31, v158
	v_readlane_b32 s61, v254, 35
	v_readlane_b32 s62, v254, 36
	v_readlane_b32 s63, v254, 37
	v_cndmask_b32_e32 v131, 0, v159, vcc
	v_cndmask_b32_e32 v130, v130, v158, vcc
	v_mov_b32_e32 v135, s63
	v_mov_b32_e32 v136, s61
	v_mov_b32_e32 v137, s62
	v_mov_b32_e32 v138, s60
	v_cndmask_b32_e32 v133, v135, v136, vcc
	v_cndmask_b32_e32 v132, v137, v138, vcc
	v_lshlrev_b64 v[130:131], 12, v[130:131]
	v_ashrrev_i32_e32 v157, 31, v156
	v_lshl_add_u64 v[130:131], v[132:133], 0, v[130:131]
	v_lshlrev_b64 v[160:161], 2, v[156:157]
	v_lshl_add_u64 v[130:131], v[130:131], 0, v[160:161]
	global_load_dwordx4 v[170:173], v[130:131], off offset:16 nt
	global_load_dwordx4 v[176:179], v[130:131], off nt
	global_load_dwordx4 v[180:183], v[130:131], off offset:528 nt
	global_load_dwordx4 v[188:191], v[130:131], off offset:512 nt
	v_add_u32_e32 v174, 16, v158
	v_cmp_gt_i32_e64 s[42:43], s79, v158
	v_add_u32_e32 v130, 0xffffc010, v158
	v_ashrrev_i32_e32 v175, 31, v174
	v_cndmask_b32_e64 v131, 0, v175, s[42:43]
	v_cndmask_b32_e64 v130, v130, v174, s[42:43]
	v_cndmask_b32_e64 v133, v135, v136, s[42:43]
	v_cndmask_b32_e64 v132, v137, v138, s[42:43]
	v_lshlrev_b64 v[130:131], 12, v[130:131]
	v_lshl_add_u64 v[130:131], v[132:133], 0, v[130:131]
	v_cmp_eq_u32_e32 vcc, 0, v134
	v_lshl_add_u64 v[134:135], v[130:131], 0, v[160:161]
	global_load_dwordx4 v[138:141], v[134:135], off offset:16 nt
	global_load_dwordx4 v[142:145], v[134:135], off nt
	global_load_dwordx4 v[130:133], v[134:135], off offset:528 nt
	s_nop 0
	global_load_dwordx4 v[134:137], v[134:135], off offset:512 nt
	v_lshlrev_b64 v[184:185], 12, v[158:159]
	v_lshl_add_u64 v[184:185], s[22:23], 0, v[184:185]
	v_lshl_add_u64 v[184:185], v[184:185], 0, v[160:161]
	v_readlane_b32 s64, v254, 38
	v_readlane_b32 s65, v254, 39
	v_readlane_b32 s66, v254, 40
	v_readlane_b32 s67, v254, 41
	v_readlane_b32 s68, v254, 42
	v_readlane_b32 s69, v254, 43
	v_readlane_b32 s70, v254, 44
	v_readlane_b32 s71, v254, 45
	v_readlane_b32 s72, v254, 46
	v_readlane_b32 s73, v254, 47
	v_readlane_b32 s74, v254, 48
	v_readlane_b32 s75, v254, 49
	s_waitcnt vmcnt(0)
	v_pk_add_f32 v[126:127], v[126:127], v[170:171]
	v_pk_add_f32 v[124:125], v[124:125], v[178:179]
	v_pk_add_f32 v[122:123], v[122:123], v[176:177]
	v_pk_add_f32 v[128:129], v[128:129], v[172:173]
	global_store_dwordx4 v[184:185], v[122:125], off
	global_store_dwordx4 v[184:185], v[126:129], off offset:16
	v_cvt_pk_bf16_f32 v170, v122, v123
	v_cvt_pk_bf16_f32 v171, v124, v125
	v_cvt_pk_bf16_f32 v172, v126, v127
	v_lshlrev_b64 v[176:177], 11, v[158:159]
	v_lshl_add_u64 v[176:177], s[6:7], 0, v[176:177]
	v_mul_f32_e32 v126, v126, v126
	v_fmac_f32_e32 v126, v122, v122
	v_mul_f32_e32 v122, v127, v127
	v_fmac_f32_e32 v122, v123, v123
	v_mul_f32_e32 v123, v128, v128
	v_add_f32_e32 v122, v126, v122
	v_fmac_f32_e32 v123, v124, v124
	v_add_f32_e32 v122, v123, v122
	v_mul_f32_e32 v123, v129, v129
	v_lshl_add_u64 v[176:177], v[156:157], 1, v[176:177]
	v_fmac_f32_e32 v123, v125, v125
	v_pk_add_f32 v[120:121], v[120:121], v[190:191]
	v_pk_add_f32 v[118:119], v[118:119], v[188:189]
	v_pk_add_f32 v[114:115], v[114:115], v[180:181]
	v_cvt_pk_bf16_f32 v173, v128, v129
	global_store_dwordx4 v[176:177], v[170:173], off
	v_add_f32_e32 v126, v123, v122
	v_pk_add_f32 v[116:117], v[116:117], v[182:183]
	global_store_dwordx4 v[184:185], v[118:121], off offset:512
	global_store_dwordx4 v[184:185], v[114:117], off offset:528
	v_cvt_pk_bf16_f32 v122, v118, v119
	v_cvt_pk_bf16_f32 v123, v120, v121
	v_cvt_pk_bf16_f32 v124, v114, v115
	v_cvt_pk_bf16_f32 v125, v116, v117
	global_store_dwordx4 v[176:177], v[122:125], off offset:256
	s_nop 0
	v_mul_f32_e32 v114, v114, v114
	v_fmac_f32_e32 v114, v118, v118
	v_mul_f32_e32 v115, v115, v115
	v_add_f32_e32 v114, v114, v126
	v_fmac_f32_e32 v115, v119, v119
	v_add_f32_e32 v114, v115, v114
	v_mul_f32_e32 v115, v116, v116
	v_fmac_f32_e32 v115, v120, v120
	v_add_f32_e32 v114, v115, v114
	v_mul_f32_e32 v115, v117, v117
	v_fmac_f32_e32 v115, v121, v121
	v_and_b32_e32 v116, 64, v203
	v_add_f32_e32 v114, v115, v114
	v_xor_b32_e32 v115, 16, v203
	v_add_u32_e32 v116, 64, v116
	v_cmp_lt_i32_e64 s[42:43], v115, v116
	s_nop 1
	v_cndmask_b32_e64 v115, v203, v115, s[42:43]
	v_lshlrev_b32_e32 v169, 2, v115
	ds_bpermute_b32 v115, v169, v114
	s_waitcnt lgkmcnt(0)
	v_add_f32_e32 v114, v114, v115
	v_xor_b32_e32 v115, 32, v203
	v_cmp_lt_i32_e64 s[42:43], v115, v116
	s_nop 1
	v_cndmask_b32_e64 v115, v203, v115, s[42:43]
	v_lshlrev_b32_e32 v170, 2, v115
	ds_bpermute_b32 v115, v170, v114
	s_and_saveexec_b64 s[16:17], vcc
	s_cbranch_execz .LBB0_50
	v_lshl_add_u64 v[116:117], v[158:159], 2, s[8:9]
	s_waitcnt lgkmcnt(0)
	v_add_f32_e32 v114, v114, v115
	global_atomic_add_f32 v[116:117], v114, off
; #define NTL(p) __builtin_nontemporal_load((const f32x4*)(p))
; #define NTS(v, p) __builtin_nontemporal_store((v), (f32x4*)(p))
; __device__ __forceinline__ unsigned cvt_pk_bf16(float lo, float hi) { unsigned r; asm volatile("v_cvt_pk_bf16_f32 %0, %1, %2" : "=v"(r) : "v"(lo), "v"(hi)); return r; }
;     __device__ __forceinline__ void operator()(AccT& acc, const Unit& u, int wr, int wc, int fr, int fq) const {
;     ...
;         for (int r = 0; r < 8; ++r) { const int ai = r >> 2, m = r & 3; const int row = row0 + ai * 128 + m * 16;
;             if (r < 7) { const int rn = row0 + ((r + 1) >> 2) * 128 + ((r + 1) & 3) * 16; const float* xr = (rn < HALF_TOK ? x0 + (size_t)rn * DM : x1 + (size_t)(rn - HALF_TOK) * DM) + col0;
;                 xv[(r + 1) & 1][0] = NTL(xr); xv[(r + 1) & 1][1] = NTL(xr + 4); xv[(r + 1) & 1][2] = NTL(xr + 128); xv[(r + 1) & 1][3] = NTL(xr + 132); }
;             float* hr = H + (size_t)row * DM + col0; float ss = 0.f;
; #pragma unroll
;             for (int bj = 0; bj < 2; ++bj) {
;                 f32x4 v0 = acc[ai][bj][m][0] + xv[r & 1][2 * bj], v1 = acc[ai][bj][m][1] + xv[r & 1][2 * bj + 1];
;                 NTS(v0, hr + bj * 128); NTS(v1, hr + bj * 128 + 4);
;                 u32x4 w; w.x = cvt_pk_bf16(v0[0], v0[1]); w.y = cvt_pk_bf16(v0[2], v0[3]); w.z = cvt_pk_bf16(v1[0], v1[1]); w.w = cvt_pk_bf16(v1[2], v1[3]);
;                 *(u32x4*)(HB + (size_t)row * DM + col0 + bj * 128) = w;
; #pragma unroll
;                 for (int j = 0; j < 4; ++j) ss += v0[j] * v0[j] + v1[j] * v1[j]; }
;             ss += __shfl_xor(ss, 16); ss += __shfl_xor(ss, 32);
;             if (fq == 0) unsafeAtomicAdd(rss + row, ss); __builtin_amdgcn_sched_barrier(0); }
.LBB0_50:
	s_or_b64 exec, exec, s[16:17]
	v_readlane_b32 s60, v254, 34
	v_add_u32_e32 v176, 32, v158
	v_readlane_b32 s61, v254, 35
	v_readlane_b32 s63, v254, 37
	v_ashrrev_i32_e32 v177, 31, v176
	v_add_u32_e32 v114, 0xffffc020, v158
	v_cmp_gt_i32_e64 s[42:43], s83, v158
	v_readlane_b32 s62, v254, 36
	v_mov_b32_e32 v116, s63
	v_mov_b32_e32 v117, s61
	s_waitcnt lgkmcnt(0)
	v_cndmask_b32_e64 v115, 0, v177, s[42:43]
	v_cndmask_b32_e64 v114, v114, v176, s[42:43]
	v_cndmask_b32_e64 v117, v116, v117, s[42:43]
	v_mov_b32_e32 v116, s62
	v_mov_b32_e32 v118, s60
	v_cndmask_b32_e64 v116, v116, v118, s[42:43]
	v_lshlrev_b64 v[114:115], 12, v[114:115]
	v_lshl_add_u64 v[114:115], v[116:117], 0, v[114:115]
	v_lshl_add_u64 v[118:119], v[114:115], 0, v[160:161]
	global_load_dwordx4 v[122:125], v[118:119], off offset:16 nt
	global_load_dwordx4 v[126:129], v[118:119], off nt
	global_load_dwordx4 v[114:117], v[118:119], off offset:528 nt
	s_nop 0
	global_load_dwordx4 v[118:121], v[118:119], off offset:512 nt
	v_lshlrev_b64 v[172:173], 12, v[174:175]
	v_lshl_add_u64 v[172:173], s[22:23], 0, v[172:173]
	v_lshl_add_u64 v[172:173], v[172:173], 0, v[160:161]
	v_pk_add_f32 v[112:113], v[112:113], v[144:145]
	v_pk_add_f32 v[110:111], v[110:111], v[142:143]
	v_pk_add_f32 v[106:107], v[106:107], v[138:139]
	v_pk_add_f32 v[108:109], v[108:109], v[140:141]
	global_store_dwordx4 v[172:173], v[110:113], off
	global_store_dwordx4 v[172:173], v[106:109], off offset:16
	v_cvt_pk_bf16_f32 v138, v110, v111
	v_cvt_pk_bf16_f32 v139, v112, v113
	v_cvt_pk_bf16_f32 v140, v106, v107
	v_pk_add_f32 v[102:103], v[102:103], v[134:135]
	v_cvt_pk_bf16_f32 v141, v108, v109
	s_nop 0
	v_mul_f32_e32 v106, v106, v106
	v_mul_f32_e32 v107, v107, v107
	v_fmac_f32_e32 v106, v110, v110
	v_fmac_f32_e32 v107, v111, v111
	v_add_f32_e32 v106, v106, v107
	v_mul_f32_e32 v107, v108, v108
	v_fmac_f32_e32 v107, v112, v112
	v_add_f32_e32 v106, v107, v106
	v_mul_f32_e32 v107, v109, v109
	v_fmac_f32_e32 v107, v113, v113
	v_add_f32_e32 v110, v107, v106
	v_pk_add_f32 v[106:107], v[98:99], v[130:131]
	v_pk_add_f32 v[108:109], v[100:101], v[132:133]
	v_mul_f32_e32 v98, v106, v106
	v_fmac_f32_e32 v98, v102, v102
	v_mul_f32_e32 v99, v107, v107
	v_add_f32_e32 v98, v98, v110
	v_fmac_f32_e32 v99, v103, v103
	v_pk_add_f32 v[104:105], v[104:105], v[136:137]
	v_add_f32_e32 v98, v99, v98
	v_mul_f32_e32 v99, v108, v108
	v_fmac_f32_e32 v99, v104, v104
	v_add_f32_e32 v98, v99, v98
	v_mul_f32_e32 v99, v109, v109
	v_fmac_f32_e32 v99, v105, v105
	v_add_f32_e32 v98, v99, v98
	ds_bpermute_b32 v99, v169, v98
	v_lshlrev_b64 v[142:143], 11, v[174:175]
	v_lshl_add_u64 v[142:143], s[6:7], 0, v[142:143]
	v_lshl_add_u64 v[142:143], v[156:157], 1, v[142:143]
	v_readlane_b32 s64, v254, 38
	s_waitcnt lgkmcnt(0)
	v_add_f32_e32 v98, v98, v99
	ds_bpermute_b32 v99, v170, v98
	v_readlane_b32 s65, v254, 39
	v_readlane_b32 s66, v254, 40
	v_readlane_b32 s67, v254, 41
	v_readlane_b32 s68, v254, 42
	v_readlane_b32 s69, v254, 43
	v_readlane_b32 s70, v254, 44
	v_readlane_b32 s71, v254, 45
	v_readlane_b32 s72, v254, 46
	v_readlane_b32 s73, v254, 47
	v_readlane_b32 s74, v254, 48
	v_readlane_b32 s75, v254, 49
	global_store_dwordx4 v[142:143], v[138:141], off
	global_store_dwordx4 v[172:173], v[102:105], off offset:512
	global_store_dwordx4 v[172:173], v[106:109], off offset:528
	v_cvt_pk_bf16_f32 v100, v102, v103
	v_cvt_pk_bf16_f32 v101, v104, v105
	s_nop 0
	v_cvt_pk_bf16_f32 v102, v106, v107
	v_cvt_pk_bf16_f32 v103, v108, v109
	global_store_dwordx4 v[142:143], v[100:103], off offset:256
	s_and_saveexec_b64 s[16:17], vcc
	s_cbranch_execz .LBB0_52
	v_lshl_add_u64 v[100:101], v[174:175], 2, s[8:9]
	s_waitcnt lgkmcnt(0)
	v_add_f32_e32 v98, v98, v99
	global_atomic_add_f32 v[100:101], v98, off
.LBB0_52:
	s_or_b64 exec, exec, s[16:17]
	v_readlane_b32 s60, v254, 34
	v_add_u32_e32 v130, 48, v158
	v_readlane_b32 s61, v254, 35
	v_readlane_b32 s63, v254, 37
	v_ashrrev_i32_e32 v131, 31, v130
	v_add_u32_e32 v98, 0xffffc030, v158
	v_cmp_gt_i32_e64 s[42:43], s84, v158
	v_readlane_b32 s62, v254, 36
	v_mov_b32_e32 v100, s63
	v_mov_b32_e32 v101, s61
	s_waitcnt lgkmcnt(0)
	v_cndmask_b32_e64 v99, 0, v131, s[42:43]
	v_cndmask_b32_e64 v98, v98, v130, s[42:43]
	v_cndmask_b32_e64 v101, v100, v101, s[42:43]
	v_mov_b32_e32 v100, s62
	v_mov_b32_e32 v102, s60
	v_cndmask_b32_e64 v100, v100, v102, s[42:43]
	v_lshlrev_b64 v[98:99], 12, v[98:99]
	v_lshl_add_u64 v[98:99], v[100:101], 0, v[98:99]
	v_lshl_add_u64 v[102:103], v[98:99], 0, v[160:161]
	global_load_dwordx4 v[106:109], v[102:103], off offset:16 nt
	global_load_dwordx4 v[110:113], v[102:103], off nt
	global_load_dwordx4 v[98:101], v[102:103], off offset:528 nt
	s_nop 0
	global_load_dwordx4 v[102:105], v[102:103], off offset:512 nt
	v_lshlrev_b64 v[132:133], 12, v[176:177]
	v_lshl_add_u64 v[132:133], s[22:23], 0, v[132:133]
	v_lshl_add_u64 v[132:133], v[132:133], 0, v[160:161]
	s_waitcnt vmcnt(12)
	v_pk_add_f32 v[96:97], v[96:97], v[128:129]
	v_pk_add_f32 v[94:95], v[94:95], v[126:127]
	v_pk_add_f32 v[90:91], v[90:91], v[122:123]
	v_pk_add_f32 v[92:93], v[92:93], v[124:125]
	global_store_dwordx4 v[132:133], v[94:97], off
	global_store_dwordx4 v[132:133], v[90:93], off offset:16
	v_cvt_pk_bf16_f32 v122, v94, v95
	v_cvt_pk_bf16_f32 v123, v96, v97
	v_cvt_pk_bf16_f32 v124, v90, v91
	s_waitcnt vmcnt(12)
; #define NTL(p) __builtin_nontemporal_load((const f32x4*)(p))
; #define NTS(v, p) __builtin_nontemporal_store((v), (f32x4*)(p))
; __device__ __forceinline__ unsigned cvt_pk_bf16(float lo, float hi) { unsigned r; asm volatile("v_cvt_pk_bf16_f32 %0, %1, %2" : "=v"(r) : "v"(lo), "v"(hi)); return r; }
;     __device__ __forceinline__ void operator()(AccT& acc, const Unit& u, int wr, int wc, int fr, int fq) const {
;     ...
;         for (int r = 0; r < 8; ++r) { const int ai = r >> 2, m = r & 3; const int row = row0 + ai * 128 + m * 16;
;             if (r < 7) { const int rn = row0 + ((r + 1) >> 2) * 128 + ((r + 1) & 3) * 16; const float* xr = (rn < HALF_TOK ? x0 + (size_t)rn * DM : x1 + (size_t)(rn - HALF_TOK) * DM) + col0;
;                 xv[(r + 1) & 1][0] = NTL(xr); xv[(r + 1) & 1][1] = NTL(xr + 4); xv[(r + 1) & 1][2] = NTL(xr + 128); xv[(r + 1) & 1][3] = NTL(xr + 132); }
;             float* hr = H + (size_t)row * DM + col0; float ss = 0.f;
; #pragma unroll
;             for (int bj = 0; bj < 2; ++bj) {
;                 f32x4 v0 = acc[ai][bj][m][0] + xv[r & 1][2 * bj], v1 = acc[ai][bj][m][1] + xv[r & 1][2 * bj + 1];
;                 NTS(v0, hr + bj * 128); NTS(v1, hr + bj * 128 + 4);
;                 u32x4 w; w.x = cvt_pk_bf16(v0[0], v0[1]); w.y = cvt_pk_bf16(v0[2], v0[3]); w.z = cvt_pk_bf16(v1[0], v1[1]); w.w = cvt_pk_bf16(v1[2], v1[3]);
;                 *(u32x4*)(HB + (size_t)row * DM + col0 + bj * 128) = w;
; #pragma unroll
;                 for (int j = 0; j < 4; ++j) ss += v0[j] * v0[j] + v1[j] * v1[j]; }
;             ss += __shfl_xor(ss, 16); ss += __shfl_xor(ss, 32);
;             if (fq == 0) unsafeAtomicAdd(rss + row, ss); __builtin_amdgcn_sched_barrier(0); }
	v_pk_add_f32 v[86:87], v[86:87], v[118:119]
	v_cvt_pk_bf16_f32 v125, v92, v93
	v_mul_f32_e32 v90, v90, v90
	v_mul_f32_e32 v91, v91, v91
	v_fmac_f32_e32 v90, v94, v94
	v_fmac_f32_e32 v91, v95, v95
	v_add_f32_e32 v90, v90, v91
	v_mul_f32_e32 v91, v92, v92
	v_fmac_f32_e32 v91, v96, v96
	v_add_f32_e32 v90, v91, v90
	v_mul_f32_e32 v91, v93, v93
	v_fmac_f32_e32 v91, v97, v97
	v_add_f32_e32 v94, v91, v90
	v_pk_add_f32 v[90:91], v[82:83], v[114:115]
	v_pk_add_f32 v[92:93], v[84:85], v[116:117]
	v_mul_f32_e32 v82, v90, v90
	v_fmac_f32_e32 v82, v86, v86
	v_mul_f32_e32 v83, v91, v91
	v_add_f32_e32 v82, v82, v94
	v_fmac_f32_e32 v83, v87, v87
	v_pk_add_f32 v[88:89], v[88:89], v[120:121]
	v_add_f32_e32 v82, v83, v82
	v_mul_f32_e32 v83, v92, v92
	v_fmac_f32_e32 v83, v88, v88
	v_add_f32_e32 v82, v83, v82
	v_mul_f32_e32 v83, v93, v93
	v_fmac_f32_e32 v83, v89, v89
	v_add_f32_e32 v82, v83, v82
	ds_bpermute_b32 v83, v169, v82
	v_lshlrev_b64 v[126:127], 11, v[176:177]
	v_lshl_add_u64 v[126:127], s[6:7], 0, v[126:127]
	v_lshl_add_u64 v[126:127], v[156:157], 1, v[126:127]
	v_readlane_b32 s64, v254, 38
	s_waitcnt lgkmcnt(0)
	v_add_f32_e32 v82, v82, v83
	ds_bpermute_b32 v83, v170, v82
	v_readlane_b32 s65, v254, 39
	v_readlane_b32 s66, v254, 40
	v_readlane_b32 s67, v254, 41
	v_readlane_b32 s68, v254, 42
	v_readlane_b32 s69, v254, 43
	v_readlane_b32 s70, v254, 44
	v_readlane_b32 s71, v254, 45
	v_readlane_b32 s72, v254, 46
	v_readlane_b32 s73, v254, 47
	v_readlane_b32 s74, v254, 48
	v_readlane_b32 s75, v254, 49
	global_store_dwordx4 v[126:127], v[122:125], off
	global_store_dwordx4 v[132:133], v[86:89], off offset:512
	global_store_dwordx4 v[132:133], v[90:93], off offset:528
	v_cvt_pk_bf16_f32 v84, v86, v87
	v_cvt_pk_bf16_f32 v85, v88, v89
	s_nop 0
	v_cvt_pk_bf16_f32 v86, v90, v91
	v_cvt_pk_bf16_f32 v87, v92, v93
	global_store_dwordx4 v[126:127], v[84:87], off offset:256
	s_and_saveexec_b64 s[16:17], vcc
	s_cbranch_execz .LBB0_54
	v_lshl_add_u64 v[84:85], v[176:177], 2, s[8:9]
	s_waitcnt lgkmcnt(0)
	v_add_f32_e32 v82, v82, v83
	global_atomic_add_f32 v[84:85], v82, off
.LBB0_54:
	s_or_b64 exec, exec, s[16:17]
	v_readlane_b32 s60, v254, 34
	v_add_u32_e32 v114, 0x80, v158
	v_readlane_b32 s61, v254, 35
	v_readlane_b32 s63, v254, 37
	v_ashrrev_i32_e32 v115, 31, v114
	v_add_u32_e32 v82, 0xffffc080, v158
	v_cmp_gt_i32_e64 s[42:43], s85, v158
	v_readlane_b32 s62, v254, 36
	v_mov_b32_e32 v84, s63
	v_mov_b32_e32 v85, s61
	s_waitcnt lgkmcnt(0)
	v_cndmask_b32_e64 v83, 0, v115, s[42:43]
	v_cndmask_b32_e64 v82, v82, v114, s[42:43]
	v_cndmask_b32_e64 v85, v84, v85, s[42:43]
	v_mov_b32_e32 v84, s62
	v_mov_b32_e32 v86, s60
	v_cndmask_b32_e64 v84, v84, v86, s[42:43]
	v_lshlrev_b64 v[82:83], 12, v[82:83]
	v_lshl_add_u64 v[82:83], v[84:85], 0, v[82:83]
	v_lshl_add_u64 v[86:87], v[82:83], 0, v[160:161]
	global_load_dwordx4 v[90:93], v[86:87], off offset:16 nt
	global_load_dwordx4 v[94:97], v[86:87], off nt
	global_load_dwordx4 v[82:85], v[86:87], off offset:528 nt
	s_nop 0
	global_load_dwordx4 v[86:89], v[86:87], off offset:512 nt
	v_lshlrev_b64 v[116:117], 12, v[130:131]
	v_lshl_add_u64 v[116:117], s[22:23], 0, v[116:117]
	v_lshl_add_u64 v[116:117], v[116:117], 0, v[160:161]
	s_waitcnt vmcnt(12)
	v_pk_add_f32 v[80:81], v[80:81], v[112:113]
	v_pk_add_f32 v[78:79], v[78:79], v[110:111]
	v_pk_add_f32 v[74:75], v[74:75], v[106:107]
	v_pk_add_f32 v[76:77], v[76:77], v[108:109]
	global_store_dwordx4 v[116:117], v[78:81], off
	global_store_dwordx4 v[116:117], v[74:77], off offset:16
	v_cvt_pk_bf16_f32 v106, v78, v79
	v_cvt_pk_bf16_f32 v107, v80, v81
	v_cvt_pk_bf16_f32 v108, v74, v75
	s_waitcnt vmcnt(12)
	v_pk_add_f32 v[70:71], v[70:71], v[102:103]
	v_cvt_pk_bf16_f32 v109, v76, v77
	v_mul_f32_e32 v74, v74, v74
	v_mul_f32_e32 v75, v75, v75
	v_fmac_f32_e32 v74, v78, v78
	v_fmac_f32_e32 v75, v79, v79
	v_add_f32_e32 v74, v74, v75
	v_mul_f32_e32 v75, v76, v76
	v_fmac_f32_e32 v75, v80, v80
	v_add_f32_e32 v74, v75, v74
	v_mul_f32_e32 v75, v77, v77
	v_fmac_f32_e32 v75, v81, v81
	v_add_f32_e32 v78, v75, v74
	v_pk_add_f32 v[74:75], v[66:67], v[98:99]
	v_pk_add_f32 v[76:77], v[68:69], v[100:101]
	v_mul_f32_e32 v66, v74, v74
	v_fmac_f32_e32 v66, v70, v70
	v_mul_f32_e32 v67, v75, v75
	v_add_f32_e32 v66, v66, v78
	v_fmac_f32_e32 v67, v71, v71
	v_pk_add_f32 v[72:73], v[72:73], v[104:105]
	v_add_f32_e32 v66, v67, v66
	v_mul_f32_e32 v67, v76, v76
	v_fmac_f32_e32 v67, v72, v72
	v_add_f32_e32 v66, v67, v66
	v_mul_f32_e32 v67, v77, v77
	v_fmac_f32_e32 v67, v73, v73
	v_add_f32_e32 v66, v67, v66
	ds_bpermute_b32 v67, v169, v66
	v_lshlrev_b64 v[110:111], 11, v[130:131]
	v_lshl_add_u64 v[110:111], s[6:7], 0, v[110:111]
	v_lshl_add_u64 v[110:111], v[156:157], 1, v[110:111]
	v_readlane_b32 s64, v254, 38
	s_waitcnt lgkmcnt(0)
	v_add_f32_e32 v66, v66, v67
	ds_bpermute_b32 v67, v170, v66
	v_readlane_b32 s65, v254, 39
	v_readlane_b32 s66, v254, 40
	v_readlane_b32 s67, v254, 41
	v_readlane_b32 s68, v254, 42
	v_readlane_b32 s69, v254, 43
	v_readlane_b32 s70, v254, 44
	v_readlane_b32 s71, v254, 45
	v_readlane_b32 s72, v254, 46
	v_readlane_b32 s73, v254, 47
	v_readlane_b32 s74, v254, 48
	v_readlane_b32 s75, v254, 49
	global_store_dwordx4 v[110:111], v[106:109], off
	global_store_dwordx4 v[116:117], v[70:73], off offset:512
	global_store_dwordx4 v[116:117], v[74:77], off offset:528
	v_cvt_pk_bf16_f32 v68, v70, v71
	v_cvt_pk_bf16_f32 v69, v72, v73
	s_nop 0
	v_cvt_pk_bf16_f32 v70, v74, v75
	v_cvt_pk_bf16_f32 v71, v76, v77
	global_store_dwordx4 v[110:111], v[68:71], off offset:256
	s_and_saveexec_b64 s[16:17], vcc
	s_cbranch_execz .LBB0_56
	v_lshl_add_u64 v[68:69], v[130:131], 2, s[8:9]
	s_waitcnt lgkmcnt(0)
	v_add_f32_e32 v66, v66, v67
	global_atomic_add_f32 v[68:69], v66, off
; #define NTL(p) __builtin_nontemporal_load((const f32x4*)(p))
; #define NTS(v, p) __builtin_nontemporal_store((v), (f32x4*)(p))
; __device__ __forceinline__ unsigned cvt_pk_bf16(float lo, float hi) { unsigned r; asm volatile("v_cvt_pk_bf16_f32 %0, %1, %2" : "=v"(r) : "v"(lo), "v"(hi)); return r; }
;     __device__ __forceinline__ void operator()(AccT& acc, const Unit& u, int wr, int wc, int fr, int fq) const {
;     ...
;         for (int r = 0; r < 8; ++r) { const int ai = r >> 2, m = r & 3; const int row = row0 + ai * 128 + m * 16;
;             if (r < 7) { const int rn = row0 + ((r + 1) >> 2) * 128 + ((r + 1) & 3) * 16; const float* xr = (rn < HALF_TOK ? x0 + (size_t)rn * DM : x1 + (size_t)(rn - HALF_TOK) * DM) + col0;
;                 xv[(r + 1) & 1][0] = NTL(xr); xv[(r + 1) & 1][1] = NTL(xr + 4); xv[(r + 1) & 1][2] = NTL(xr + 128); xv[(r + 1) & 1][3] = NTL(xr + 132); }
;             float* hr = H + (size_t)row * DM + col0; float ss = 0.f;
; #pragma unroll
;             for (int bj = 0; bj < 2; ++bj) {
;                 f32x4 v0 = acc[ai][bj][m][0] + xv[r & 1][2 * bj], v1 = acc[ai][bj][m][1] + xv[r & 1][2 * bj + 1];
;                 NTS(v0, hr + bj * 128); NTS(v1, hr + bj * 128 + 4);
;                 u32x4 w; w.x = cvt_pk_bf16(v0[0], v0[1]); w.y = cvt_pk_bf16(v0[2], v0[3]); w.z = cvt_pk_bf16(v1[0], v1[1]); w.w = cvt_pk_bf16(v1[2], v1[3]);
;                 *(u32x4*)(HB + (size_t)row * DM + col0 + bj * 128) = w;
; #pragma unroll
;                 for (int j = 0; j < 4; ++j) ss += v0[j] * v0[j] + v1[j] * v1[j]; }
;             ss += __shfl_xor(ss, 16); ss += __shfl_xor(ss, 32);
;             if (fq == 0) unsafeAtomicAdd(rss + row, ss); __builtin_amdgcn_sched_barrier(0); }
.LBB0_56:
	s_or_b64 exec, exec, s[16:17]
	v_readlane_b32 s60, v254, 34
	v_add_u32_e32 v98, 0x90, v158
	v_readlane_b32 s61, v254, 35
	v_readlane_b32 s63, v254, 37
	v_ashrrev_i32_e32 v99, 31, v98
	v_add_u32_e32 v66, 0xffffc090, v158
	v_cmp_gt_i32_e64 s[42:43], s86, v158
	v_readlane_b32 s62, v254, 36
	v_mov_b32_e32 v68, s63
	v_mov_b32_e32 v69, s61
	s_waitcnt lgkmcnt(0)
	v_cndmask_b32_e64 v67, 0, v99, s[42:43]
	v_cndmask_b32_e64 v66, v66, v98, s[42:43]
	v_cndmask_b32_e64 v69, v68, v69, s[42:43]
	v_mov_b32_e32 v68, s62
	v_mov_b32_e32 v70, s60
	v_cndmask_b32_e64 v68, v68, v70, s[42:43]
	v_lshlrev_b64 v[66:67], 12, v[66:67]
	v_lshl_add_u64 v[66:67], v[68:69], 0, v[66:67]
	v_lshl_add_u64 v[70:71], v[66:67], 0, v[160:161]
	global_load_dwordx4 v[74:77], v[70:71], off offset:16 nt
	global_load_dwordx4 v[78:81], v[70:71], off nt
	global_load_dwordx4 v[66:69], v[70:71], off offset:528 nt
	s_nop 0
	global_load_dwordx4 v[70:73], v[70:71], off offset:512 nt
	v_lshlrev_b64 v[100:101], 12, v[114:115]
	v_lshl_add_u64 v[100:101], s[22:23], 0, v[100:101]
	v_lshl_add_u64 v[100:101], v[100:101], 0, v[160:161]
	s_waitcnt vmcnt(12)
	v_pk_add_f32 v[64:65], v[64:65], v[96:97]
	v_pk_add_f32 v[62:63], v[62:63], v[94:95]
	v_pk_add_f32 v[58:59], v[58:59], v[90:91]
	v_pk_add_f32 v[60:61], v[60:61], v[92:93]
	global_store_dwordx4 v[100:101], v[62:65], off
	global_store_dwordx4 v[100:101], v[58:61], off offset:16
	v_cvt_pk_bf16_f32 v90, v62, v63
	v_cvt_pk_bf16_f32 v91, v64, v65
	v_cvt_pk_bf16_f32 v92, v58, v59
	s_waitcnt vmcnt(12)
	v_pk_add_f32 v[54:55], v[54:55], v[86:87]
	v_cvt_pk_bf16_f32 v93, v60, v61
	v_mul_f32_e32 v58, v58, v58
	v_mul_f32_e32 v59, v59, v59
	v_fmac_f32_e32 v58, v62, v62
	v_fmac_f32_e32 v59, v63, v63
	v_add_f32_e32 v58, v58, v59
	v_mul_f32_e32 v59, v60, v60
	v_fmac_f32_e32 v59, v64, v64
	v_add_f32_e32 v58, v59, v58
	v_mul_f32_e32 v59, v61, v61
	v_fmac_f32_e32 v59, v65, v65
	v_add_f32_e32 v62, v59, v58
	v_pk_add_f32 v[58:59], v[50:51], v[82:83]
	v_pk_add_f32 v[60:61], v[52:53], v[84:85]
	v_mul_f32_e32 v50, v58, v58
	v_fmac_f32_e32 v50, v54, v54
	v_mul_f32_e32 v51, v59, v59
	v_add_f32_e32 v50, v50, v62
	v_fmac_f32_e32 v51, v55, v55
	v_pk_add_f32 v[56:57], v[56:57], v[88:89]
	v_add_f32_e32 v50, v51, v50
	v_mul_f32_e32 v51, v60, v60
	v_fmac_f32_e32 v51, v56, v56
	v_add_f32_e32 v50, v51, v50
	v_mul_f32_e32 v51, v61, v61
	v_fmac_f32_e32 v51, v57, v57
	v_add_f32_e32 v50, v51, v50
	ds_bpermute_b32 v51, v169, v50
	v_lshlrev_b64 v[94:95], 11, v[114:115]
	v_lshl_add_u64 v[94:95], s[6:7], 0, v[94:95]
	v_lshl_add_u64 v[94:95], v[156:157], 1, v[94:95]
	v_readlane_b32 s64, v254, 38
	s_waitcnt lgkmcnt(0)
	v_add_f32_e32 v50, v50, v51
	ds_bpermute_b32 v51, v170, v50
	v_readlane_b32 s65, v254, 39
	v_readlane_b32 s66, v254, 40
	v_readlane_b32 s67, v254, 41
	v_readlane_b32 s68, v254, 42
	v_readlane_b32 s69, v254, 43
	v_readlane_b32 s70, v254, 44
	v_readlane_b32 s71, v254, 45
	v_readlane_b32 s72, v254, 46
	v_readlane_b32 s73, v254, 47
	v_readlane_b32 s74, v254, 48
	v_readlane_b32 s75, v254, 49
	global_store_dwordx4 v[94:95], v[90:93], off
	global_store_dwordx4 v[100:101], v[54:57], off offset:512
	global_store_dwordx4 v[100:101], v[58:61], off offset:528
	v_cvt_pk_bf16_f32 v52, v54, v55
	v_cvt_pk_bf16_f32 v53, v56, v57
	s_nop 0
	v_cvt_pk_bf16_f32 v54, v58, v59
	v_cvt_pk_bf16_f32 v55, v60, v61
	global_store_dwordx4 v[94:95], v[52:55], off offset:256
	s_and_saveexec_b64 s[16:17], vcc
	s_cbranch_execz .LBB0_58
	v_lshl_add_u64 v[52:53], v[114:115], 2, s[8:9]
	s_waitcnt lgkmcnt(0)
	v_add_f32_e32 v50, v50, v51
	global_atomic_add_f32 v[52:53], v50, off
.LBB0_58:
	s_or_b64 exec, exec, s[16:17]
	v_readlane_b32 s60, v254, 34
	v_add_u32_e32 v82, 0xa0, v158
	v_readlane_b32 s61, v254, 35
	v_readlane_b32 s63, v254, 37
	v_ashrrev_i32_e32 v83, 31, v82
	v_add_u32_e32 v50, 0xffffc0a0, v158
	v_cmp_gt_i32_e64 s[42:43], s87, v158
	v_readlane_b32 s62, v254, 36
	v_mov_b32_e32 v52, s63
	v_mov_b32_e32 v53, s61
	s_waitcnt lgkmcnt(0)
	v_cndmask_b32_e64 v51, 0, v83, s[42:43]
	v_cndmask_b32_e64 v50, v50, v82, s[42:43]
	v_cndmask_b32_e64 v53, v52, v53, s[42:43]
	v_mov_b32_e32 v52, s62
	v_mov_b32_e32 v54, s60
	v_cndmask_b32_e64 v52, v52, v54, s[42:43]
	v_lshlrev_b64 v[50:51], 12, v[50:51]
	v_lshl_add_u64 v[50:51], v[52:53], 0, v[50:51]
	v_lshl_add_u64 v[54:55], v[50:51], 0, v[160:161]
	global_load_dwordx4 v[58:61], v[54:55], off offset:16 nt
	global_load_dwordx4 v[62:65], v[54:55], off nt
	global_load_dwordx4 v[50:53], v[54:55], off offset:528 nt
	s_nop 0
	global_load_dwordx4 v[54:57], v[54:55], off offset:512 nt
	v_lshlrev_b64 v[84:85], 12, v[98:99]
	v_lshl_add_u64 v[84:85], s[22:23], 0, v[84:85]
	v_lshl_add_u64 v[84:85], v[84:85], 0, v[160:161]
	s_waitcnt vmcnt(12)
	v_pk_add_f32 v[48:49], v[48:49], v[80:81]
	v_pk_add_f32 v[46:47], v[46:47], v[78:79]
	v_pk_add_f32 v[42:43], v[42:43], v[74:75]
	v_pk_add_f32 v[44:45], v[44:45], v[76:77]
	global_store_dwordx4 v[84:85], v[46:49], off
	global_store_dwordx4 v[84:85], v[42:45], off offset:16
	v_cvt_pk_bf16_f32 v74, v46, v47
	v_cvt_pk_bf16_f32 v75, v48, v49
	v_cvt_pk_bf16_f32 v76, v42, v43
	s_waitcnt vmcnt(12)
	v_pk_add_f32 v[38:39], v[38:39], v[70:71]
	v_cvt_pk_bf16_f32 v77, v44, v45
	v_mul_f32_e32 v42, v42, v42
	v_mul_f32_e32 v43, v43, v43
	v_fmac_f32_e32 v42, v46, v46
	v_fmac_f32_e32 v43, v47, v47
	v_add_f32_e32 v42, v42, v43
	v_mul_f32_e32 v43, v44, v44
	v_fmac_f32_e32 v43, v48, v48
	v_add_f32_e32 v42, v43, v42
	v_mul_f32_e32 v43, v45, v45
	v_fmac_f32_e32 v43, v49, v49
	v_add_f32_e32 v46, v43, v42
	v_pk_add_f32 v[42:43], v[34:35], v[66:67]
	v_pk_add_f32 v[44:45], v[36:37], v[68:69]
	v_mul_f32_e32 v34, v42, v42
	v_fmac_f32_e32 v34, v38, v38
	v_mul_f32_e32 v35, v43, v43
	v_add_f32_e32 v34, v34, v46
	v_fmac_f32_e32 v35, v39, v39
	v_pk_add_f32 v[40:41], v[40:41], v[72:73]
	v_add_f32_e32 v34, v35, v34
	v_mul_f32_e32 v35, v44, v44
	v_fmac_f32_e32 v35, v40, v40
	v_add_f32_e32 v34, v35, v34
	v_mul_f32_e32 v35, v45, v45
	v_fmac_f32_e32 v35, v41, v41
	v_add_f32_e32 v34, v35, v34
	ds_bpermute_b32 v35, v169, v34
	v_lshlrev_b64 v[78:79], 11, v[98:99]
	v_lshl_add_u64 v[78:79], s[6:7], 0, v[78:79]
	v_lshl_add_u64 v[78:79], v[156:157], 1, v[78:79]
	v_readlane_b32 s64, v254, 38
	s_waitcnt lgkmcnt(0)
	v_add_f32_e32 v34, v34, v35
	ds_bpermute_b32 v35, v170, v34
	v_readlane_b32 s65, v254, 39
	v_readlane_b32 s66, v254, 40
	v_readlane_b32 s67, v254, 41
	v_readlane_b32 s68, v254, 42
	v_readlane_b32 s69, v254, 43
	v_readlane_b32 s70, v254, 44
	v_readlane_b32 s71, v254, 45
	v_readlane_b32 s72, v254, 46
	v_readlane_b32 s73, v254, 47
	v_readlane_b32 s74, v254, 48
	v_readlane_b32 s75, v254, 49
	global_store_dwordx4 v[78:79], v[74:77], off
	global_store_dwordx4 v[84:85], v[38:41], off offset:512
	global_store_dwordx4 v[84:85], v[42:45], off offset:528
	v_cvt_pk_bf16_f32 v36, v38, v39
	v_cvt_pk_bf16_f32 v37, v40, v41
	s_nop 0
	v_cvt_pk_bf16_f32 v38, v42, v43
	v_cvt_pk_bf16_f32 v39, v44, v45
	global_store_dwordx4 v[78:79], v[36:39], off offset:256
	s_and_saveexec_b64 s[16:17], vcc
	s_cbranch_execz .LBB0_60
; #define NTL(p) __builtin_nontemporal_load((const f32x4*)(p))
; #define NTS(v, p) __builtin_nontemporal_store((v), (f32x4*)(p))
; __device__ __forceinline__ unsigned cvt_pk_bf16(float lo, float hi) { unsigned r; asm volatile("v_cvt_pk_bf16_f32 %0, %1, %2" : "=v"(r) : "v"(lo), "v"(hi)); return r; }
;     __device__ __forceinline__ void operator()(AccT& acc, const Unit& u, int wr, int wc, int fr, int fq) const {
;     ...
;         for (int r = 0; r < 8; ++r) { const int ai = r >> 2, m = r & 3; const int row = row0 + ai * 128 + m * 16;
;             if (r < 7) { const int rn = row0 + ((r + 1) >> 2) * 128 + ((r + 1) & 3) * 16; const float* xr = (rn < HALF_TOK ? x0 + (size_t)rn * DM : x1 + (size_t)(rn - HALF_TOK) * DM) + col0;
;                 xv[(r + 1) & 1][0] = NTL(xr); xv[(r + 1) & 1][1] = NTL(xr + 4); xv[(r + 1) & 1][2] = NTL(xr + 128); xv[(r + 1) & 1][3] = NTL(xr + 132); }
;             float* hr = H + (size_t)row * DM + col0; float ss = 0.f;
; #pragma unroll
;             for (int bj = 0; bj < 2; ++bj) {
;                 f32x4 v0 = acc[ai][bj][m][0] + xv[r & 1][2 * bj], v1 = acc[ai][bj][m][1] + xv[r & 1][2 * bj + 1];
;                 NTS(v0, hr + bj * 128); NTS(v1, hr + bj * 128 + 4);
;                 u32x4 w; w.x = cvt_pk_bf16(v0[0], v0[1]); w.y = cvt_pk_bf16(v0[2], v0[3]); w.z = cvt_pk_bf16(v1[0], v1[1]); w.w = cvt_pk_bf16(v1[2], v1[3]);
;                 *(u32x4*)(HB + (size_t)row * DM + col0 + bj * 128) = w;
; #pragma unroll
;                 for (int j = 0; j < 4; ++j) ss += v0[j] * v0[j] + v1[j] * v1[j]; }
;             ss += __shfl_xor(ss, 16); ss += __shfl_xor(ss, 32);
;             if (fq == 0) unsafeAtomicAdd(rss + row, ss); __builtin_amdgcn_sched_barrier(0); }
	v_lshl_add_u64 v[36:37], v[98:99], 2, s[8:9]
	s_waitcnt lgkmcnt(0)
	v_add_f32_e32 v34, v34, v35
	global_atomic_add_f32 v[36:37], v34, off
.LBB0_60:
	s_or_b64 exec, exec, s[16:17]
	v_readlane_b32 s60, v254, 34
	v_add_u32_e32 v66, 0xb0, v158
	v_readlane_b32 s61, v254, 35
	v_readlane_b32 s63, v254, 37
	v_ashrrev_i32_e32 v67, 31, v66
	v_add_u32_e32 v34, 0xffffc0b0, v158
	v_cmp_gt_i32_e64 s[42:43], s88, v158
	v_readlane_b32 s62, v254, 36
	v_mov_b32_e32 v36, s63
	v_mov_b32_e32 v37, s61
	s_waitcnt lgkmcnt(0)
	v_cndmask_b32_e64 v35, 0, v67, s[42:43]
	v_cndmask_b32_e64 v34, v34, v66, s[42:43]
	v_cndmask_b32_e64 v37, v36, v37, s[42:43]
	v_mov_b32_e32 v36, s62
	v_mov_b32_e32 v38, s60
	v_cndmask_b32_e64 v36, v36, v38, s[42:43]
	v_lshlrev_b64 v[34:35], 12, v[34:35]
	v_lshl_add_u64 v[34:35], v[36:37], 0, v[34:35]
	v_lshl_add_u64 v[38:39], v[34:35], 0, v[160:161]
	global_load_dwordx4 v[42:45], v[38:39], off offset:16 nt
	global_load_dwordx4 v[46:49], v[38:39], off nt
	global_load_dwordx4 v[34:37], v[38:39], off offset:528 nt
	s_nop 0
	global_load_dwordx4 v[38:41], v[38:39], off offset:512 nt
	v_lshlrev_b64 v[68:69], 12, v[82:83]
	v_lshl_add_u64 v[68:69], s[22:23], 0, v[68:69]
	v_lshl_add_u64 v[68:69], v[68:69], 0, v[160:161]
	s_waitcnt vmcnt(12)
	v_pk_add_f32 v[32:33], v[32:33], v[64:65]
	v_pk_add_f32 v[30:31], v[30:31], v[62:63]
	v_pk_add_f32 v[26:27], v[26:27], v[58:59]
	v_pk_add_f32 v[28:29], v[28:29], v[60:61]
	global_store_dwordx4 v[68:69], v[30:33], off
	global_store_dwordx4 v[68:69], v[26:29], off offset:16
	v_cvt_pk_bf16_f32 v58, v30, v31
	v_cvt_pk_bf16_f32 v59, v32, v33
	v_cvt_pk_bf16_f32 v60, v26, v27
	s_waitcnt vmcnt(12)
	v_pk_add_f32 v[22:23], v[22:23], v[54:55]
	v_cvt_pk_bf16_f32 v61, v28, v29
	v_mul_f32_e32 v26, v26, v26
	v_mul_f32_e32 v27, v27, v27
	v_fmac_f32_e32 v26, v30, v30
	v_fmac_f32_e32 v27, v31, v31
	v_add_f32_e32 v26, v26, v27
	v_mul_f32_e32 v27, v28, v28
	v_fmac_f32_e32 v27, v32, v32
	v_add_f32_e32 v26, v27, v26
	v_mul_f32_e32 v27, v29, v29
	v_fmac_f32_e32 v27, v33, v33
	v_add_f32_e32 v30, v27, v26
	v_pk_add_f32 v[26:27], v[18:19], v[50:51]
	v_pk_add_f32 v[28:29], v[20:21], v[52:53]
	v_mul_f32_e32 v18, v26, v26
	v_fmac_f32_e32 v18, v22, v22
	v_mul_f32_e32 v19, v27, v27
	v_add_f32_e32 v18, v18, v30
	v_fmac_f32_e32 v19, v23, v23
	v_pk_add_f32 v[24:25], v[24:25], v[56:57]
	v_add_f32_e32 v18, v19, v18
	v_mul_f32_e32 v19, v28, v28
	v_fmac_f32_e32 v19, v24, v24
	v_add_f32_e32 v18, v19, v18
	v_mul_f32_e32 v19, v29, v29
	v_fmac_f32_e32 v19, v25, v25
	v_add_f32_e32 v18, v19, v18
	ds_bpermute_b32 v19, v169, v18
	v_lshlrev_b64 v[62:63], 11, v[82:83]
	v_lshl_add_u64 v[62:63], s[6:7], 0, v[62:63]
	v_lshl_add_u64 v[62:63], v[156:157], 1, v[62:63]
	v_readlane_b32 s64, v254, 38
	s_waitcnt lgkmcnt(0)
	v_add_f32_e32 v18, v18, v19
	ds_bpermute_b32 v19, v170, v18
	v_readlane_b32 s65, v254, 39
	v_readlane_b32 s66, v254, 40
	v_readlane_b32 s67, v254, 41
	v_readlane_b32 s68, v254, 42
	v_readlane_b32 s69, v254, 43
	v_readlane_b32 s70, v254, 44
	v_readlane_b32 s71, v254, 45
	v_readlane_b32 s72, v254, 46
	v_readlane_b32 s73, v254, 47
	v_readlane_b32 s74, v254, 48
	v_readlane_b32 s75, v254, 49
	global_store_dwordx4 v[62:63], v[58:61], off
	global_store_dwordx4 v[68:69], v[22:25], off offset:512
	global_store_dwordx4 v[68:69], v[26:29], off offset:528
	v_cvt_pk_bf16_f32 v20, v22, v23
	v_cvt_pk_bf16_f32 v21, v24, v25
	s_nop 0
	v_cvt_pk_bf16_f32 v22, v26, v27
	v_cvt_pk_bf16_f32 v23, v28, v29
	global_store_dwordx4 v[62:63], v[20:23], off offset:256
	s_and_saveexec_b64 s[16:17], vcc
	s_cbranch_execz .LBB0_62
	v_lshl_add_u64 v[20:21], v[82:83], 2, s[8:9]
	s_waitcnt lgkmcnt(0)
	v_add_f32_e32 v18, v18, v19
	global_atomic_add_f32 v[20:21], v18, off
.LBB0_62:
	s_or_b64 exec, exec, s[16:17]
	s_waitcnt lgkmcnt(0)
	v_lshlrev_b64 v[18:19], 12, v[66:67]
	v_lshl_add_u64 v[18:19], s[22:23], 0, v[18:19]
	v_lshl_add_u64 v[22:23], v[156:157], 2, v[18:19]
	s_waitcnt vmcnt(8)
	v_pk_add_f32 v[16:17], v[16:17], v[48:49]
	v_pk_add_f32 v[14:15], v[14:15], v[46:47]
	v_pk_add_f32 v[10:11], v[10:11], v[42:43]
	v_pk_add_f32 v[12:13], v[12:13], v[44:45]
	global_store_dwordx4 v[22:23], v[14:17], off
	global_store_dwordx4 v[22:23], v[10:13], off offset:16
	v_cvt_pk_bf16_f32 v18, v14, v15
	v_cvt_pk_bf16_f32 v19, v16, v17
	v_cvt_pk_bf16_f32 v20, v10, v11
	s_waitcnt vmcnt(8)
	v_pk_add_f32 v[6:7], v[6:7], v[38:39]
	v_cvt_pk_bf16_f32 v21, v12, v13
	v_mul_f32_e32 v10, v10, v10
	v_mul_f32_e32 v11, v11, v11
	v_fmac_f32_e32 v10, v14, v14
	v_fmac_f32_e32 v11, v15, v15
	v_add_f32_e32 v10, v10, v11
	v_mul_f32_e32 v11, v12, v12
	v_fmac_f32_e32 v11, v16, v16
	v_add_f32_e32 v10, v11, v10
	v_mul_f32_e32 v11, v13, v13
	v_fmac_f32_e32 v11, v17, v17
	v_add_f32_e32 v14, v11, v10
	v_pk_add_f32 v[10:11], v[2:3], v[34:35]
	v_pk_add_f32 v[12:13], v[4:5], v[36:37]
	v_mul_f32_e32 v2, v10, v10
	v_fmac_f32_e32 v2, v6, v6
	v_mul_f32_e32 v3, v11, v11
	v_add_f32_e32 v2, v2, v14
	v_fmac_f32_e32 v3, v7, v7
	v_pk_add_f32 v[8:9], v[8:9], v[40:41]
	v_add_f32_e32 v2, v3, v2
	v_mul_f32_e32 v3, v12, v12
	v_fmac_f32_e32 v3, v8, v8
	v_add_f32_e32 v2, v3, v2
	v_mul_f32_e32 v3, v13, v13
	v_fmac_f32_e32 v3, v9, v9
	v_add_f32_e32 v2, v3, v2
	ds_bpermute_b32 v3, v169, v2
	v_lshlrev_b64 v[24:25], 11, v[66:67]
	v_lshl_add_u64 v[24:25], s[6:7], 0, v[24:25]
	v_lshl_add_u64 v[24:25], v[156:157], 1, v[24:25]
	global_store_dwordx4 v[24:25], v[18:21], off
	global_store_dwordx4 v[22:23], v[6:9], off offset:512
	global_store_dwordx4 v[22:23], v[10:13], off offset:528
	s_waitcnt lgkmcnt(0)
	v_add_f32_e32 v2, v2, v3
	ds_bpermute_b32 v3, v170, v2
	v_cvt_pk_bf16_f32 v4, v6, v7
	v_cvt_pk_bf16_f32 v5, v8, v9
	v_cvt_pk_bf16_f32 v6, v10, v11
	v_cvt_pk_bf16_f32 v7, v12, v13
	global_store_dwordx4 v[24:25], v[4:7], off offset:256
	s_and_saveexec_b64 s[16:17], vcc
	s_cbranch_execz .LBB0_34
	v_lshl_add_u64 v[4:5], v[66:67], 2, s[8:9]
	s_waitcnt lgkmcnt(0)
	v_add_f32_e32 v2, v2, v3
	global_atomic_add_f32 v[4:5], v2, off
	s_branch .LBB0_34
